# P2: triangular-inverse forward substitution (wave 0) rewritten with all L rows requested up to 15 reads ahead into dead registers; identical arithmetic order
# speedup vs baseline: 1.0082x; 1.0082x over previous
; __device__ __forceinline__ unsigned pk2(float lo, float hi) { f32x2_t v = {lo, hi}; bf16x2_t b = __builtin_convertvector(v, bf16x2_t); return __builtin_bit_cast(unsigned, b); }
; __device__ void rwkv_prep_item(const Params& p, char* lds_, int item, PrepRaw& raw, int next_item) {
;     ...
;     u32x4 w;
;     w.x = pk2(bon * vv[0], bon * vv[1]); w.y = pk2(bon * vv[2], bon * vv[3]); w.z = pk2(bon * vv[4], bon * vv[5]); w.w = pk2(bon * vv[6], bon * vv[7]);
;     *(u32x4*)(p.BV + (size_t)item * 4096 + t * 64 + cg8) = w;
;   }
;   __syncthreads();
;   {
;     f32x4 lab[2], lak[2], mrb[2], mrk[2]; zero2(lab); zero2(lak); zero2(mrb); zero2(mrk);
;     mm_nt(At, Bt, lab, wave, lane);
;     mm_nt(At, Kt, lak, wave, lane);
;     mm_nt(Rt, Bt, mrb, wave, lane);
;     mm_nt(Rt, Kt, mrk, wave, lane);
; #pragma unroll
;     for (int jj = 0; jj < 2; ++jj) {
;       const int j0 = (jt0 + jj) * 16 + 4 * mg;
;       f32x4 o; float x1[4], x2[4], x3[4];
; #pragma unroll
;       for (int e = 0; e < 4; ++e) {
;         const int j = j0 + e;
;         o[e] = (j < mi) ? lab[jj][e] : 0.f;
;         x1[e] = (j < mi) ? lak[jj][e] : 0.f;
;         x2[e] = (j <= mi) ? mrb[jj][e] : 0.f;
;         x3[e] = (j <= mi) ? mrk[jj][e] : 0.f;
;       }
;       *(f32x4*)(Tf + mi * 68 + j0) = o;
;       u32x2 w;
;       w.x = pk2(x1[0], x1[1]); w.y = pk2(x1[2], x1[3]); *(u32x2*)(LAK + mi * LD + j0) = w;
;       w.x = pk2(x2[0], x2[1]); w.y = pk2(x2[2], x2[3]); *(u32x2*)(MRB + mi * LD + j0) = w;
;       w.x = pk2(x3[0], x3[1]); w.y = pk2(x3[2], x3[3]); *(u32x2*)(MRK + mi * LD + j0) = w;
;     }
;   }
;   __syncthreads();
;   {
;     float* Ms = Za;
;     const int r16 = lane & 15, g4 = lane >> 4;
;     if (wave == 0) {
.LBB0_321:
	v_add_f32_e32 v28, v48, v49
	v_pk_mul_f32 v[24:25], v[30:31], v[28:29] op_sel_hi:[1,0]
	v_pk_mul_f32 v[18:19], v[18:19], v[28:29] op_sel_hi:[1,0]
	v_cvt_pk_bf16_f32 v24, v24, v25
	v_cvt_pk_bf16_f32 v25, v18, v19
	v_pk_mul_f32 v[18:19], v[22:23], v[28:29] op_sel_hi:[1,0]
	s_ashr_i32 s55, s54, 31
	v_cvt_pk_bf16_f32 v26, v18, v19
	v_pk_mul_f32 v[18:19], v[20:21], v[28:29] op_sel_hi:[1,0]
	s_lshl_b64 s[58:59], s[54:55], 13
	v_cvt_pk_bf16_f32 v27, v18, v19
	v_lshl_add_u64 v[18:19], v[138:139], 0, s[58:59]
	global_store_dwordx4 v[18:19], v[24:27], off
	s_waitcnt lgkmcnt(0)
	s_barrier
	ds_read_b128 v[18:21], v188 offset:9472
	ds_read_b128 v[22:25], v187 offset:256
	ds_read_b128 v[26:29], v187 offset:320
	ds_read_b128 v[30:33], v188 offset:9536
	ds_read_b128 v[38:41], v188 offset:11776
	ds_read_b128 v[46:49], v188 offset:11840
	ds_read_b128 v[54:57], v188 offset:18688
	ds_read_b128 v[58:61], v188 offset:18752
	ds_read_b128 v[66:69], v187 offset:27904
	ds_read_b128 v[70:73], v187 offset:27968
	s_waitcnt lgkmcnt(8)
	v_mfma_f32_16x16x32_bf16 v[34:37], v[18:21], v[22:25], 0
	s_waitcnt lgkmcnt(1)
	v_mfma_f32_16x16x32_bf16 v[18:21], v[18:21], v[66:69], 0
	v_mfma_f32_16x16x32_bf16 v[34:37], v[30:33], v[26:29], v[34:37]
	v_mfma_f32_16x16x32_bf16 v[62:65], v[54:57], v[22:25], 0
	s_waitcnt lgkmcnt(0)
	v_mfma_f32_16x16x32_bf16 v[18:21], v[30:33], v[70:73], v[18:21]
	s_nop 4
	v_cndmask_b32_e64 v34, 0, v34, s[14:15]
	v_cndmask_b32_e64 v35, 0, v35, s[18:19]
	v_cndmask_b32_e64 v36, 0, v36, s[20:21]
	v_mfma_f32_16x16x32_bf16 v[30:33], v[54:57], v[66:69], 0
	ds_read_b128 v[54:57], v188 offset:20992
	ds_read_b128 v[74:77], v188 offset:21056
	v_cndmask_b32_e64 v37, 0, v37, s[24:25]
	ds_write_b128 v229, v[34:37]
	v_mfma_f32_16x16x32_bf16 v[50:53], v[38:41], v[22:25], 0
	s_waitcnt lgkmcnt(2)
	v_mfma_f32_16x16x32_bf16 v[22:25], v[54:57], v[22:25], 0
	v_mfma_f32_16x16x32_bf16 v[50:53], v[46:49], v[26:29], v[50:53]
	v_mfma_f32_16x16x32_bf16 v[62:65], v[58:61], v[26:29], v[62:65]
	v_mfma_f32_16x16x32_bf16 v[30:33], v[58:61], v[70:73], v[30:33]
	v_cndmask_b32_e64 v59, v18, 0, s[16:17]
	v_cndmask_b32_e64 v61, 0, v19, s[14:15]
	s_nop 4
	v_cndmask_b32_e64 v58, 0, v62, s[14:15]
	s_waitcnt lgkmcnt(1)
	v_mfma_f32_16x16x32_bf16 v[22:25], v[74:77], v[26:29], v[22:25]
	v_mfma_f32_16x16x32_bf16 v[26:29], v[38:41], v[66:69], 0
	v_cndmask_b32_e64 v38, v20, 0, s[22:23]
	v_cndmask_b32_e64 v40, v21, 0, s[26:27]
	v_cndmask_b32_e64 v60, v30, 0, s[16:17]
	v_mfma_f32_16x16x32_bf16 v[18:21], v[54:57], v[66:69], 0
	v_cndmask_b32_e64 v30, 0, v63, s[18:19]
	v_cndmask_b32_e64 v62, 0, v31, s[14:15]
	v_cndmask_b32_e64 v31, 0, v64, s[20:21]
	v_mfma_f32_16x16x32_bf16 v[26:29], v[46:49], v[70:73], v[26:29]
	v_cndmask_b32_e64 v39, 0, v65, s[24:25]
	v_cvt_pk_bf16_f32 v30, v58, v30
	v_cvt_pk_bf16_f32 v31, v31, v39
	v_mfma_f32_16x16x32_bf16 v[18:21], v[74:77], v[70:73], v[18:21]
	v_cndmask_b32_e64 v32, v32, 0, s[22:23]
	v_cndmask_b32_e64 v33, v33, 0, s[26:27]
	ds_write_b64 v230, v[30:31]
	v_cvt_pk_bf16_f32 v30, v59, v61
	v_cvt_pk_bf16_f32 v31, v38, v40
	ds_write_b64 v231, v[30:31]
	v_cvt_pk_bf16_f32 v30, v60, v62
	v_cvt_pk_bf16_f32 v31, v32, v33
	v_cndmask_b32_e64 v22, 0, v22, s[28:29]
	v_cndmask_b32_e64 v34, v18, 0, s[30:31]
	v_cndmask_b32_e64 v18, 0, v23, s[34:35]
	v_cndmask_b32_e64 v23, 0, v27, s[28:29]
	v_cndmask_b32_e64 v27, 0, v19, s[28:29]
	v_cndmask_b32_e64 v19, 0, v24, s[36:37]
	v_cndmask_b32_e64 v25, 0, v25, s[40:41]
	ds_write_b64 v232, v[30:31]
	v_cndmask_b32_e64 v30, 0, v50, s[28:29]
	v_cndmask_b32_e64 v26, v26, 0, s[30:31]
	v_cndmask_b32_e64 v31, 0, v51, s[34:35]
	v_cndmask_b32_e64 v32, 0, v52, s[36:37]
	v_cndmask_b32_e64 v24, v28, 0, s[38:39]
	v_cndmask_b32_e64 v33, 0, v53, s[40:41]
	v_cndmask_b32_e64 v28, v29, 0, s[42:43]
	v_cvt_pk_bf16_f32 v18, v22, v18
	v_cvt_pk_bf16_f32 v19, v19, v25
	v_cndmask_b32_e64 v20, v20, 0, s[38:39]
	v_cndmask_b32_e64 v21, v21, 0, s[42:43]
	ds_write_b128 v235, v[30:33]
	ds_write_b64 v236, v[18:19]
	v_cvt_pk_bf16_f32 v18, v26, v23
	v_cvt_pk_bf16_f32 v19, v24, v28
	ds_write_b64 v237, v[18:19]
	v_cvt_pk_bf16_f32 v18, v34, v27
	v_cvt_pk_bf16_f32 v19, v20, v21
	ds_write_b64 v238, v[18:19]
	s_waitcnt lgkmcnt(0)
	s_barrier
	s_and_saveexec_b64 s[58:59], s[4:5]
	s_cbranch_execz .LBB0_323
; __device__ void rwkv_prep_item(const Params& p, char* lds_, int item, PrepRaw& raw, int next_item) {
;     ...
;     if (wave == 0) {
;       const float* Lk = Tf + (16 * g4) * 68 + 16 * g4;
;       float xv[16];
; #pragma unroll
;       for (int i = 0; i < 16; ++i) {
;         float sacc = (i == r16) ? 1.f : 0.f;
; #pragma unroll
;         for (int q = 0; q < (i + 3) / 4; ++q) {
;           const f32x4 Lv = *(const f32x4*)(Lk + i * 68 + 4 * q);
; #pragma unroll
;           for (int e = 0; e < 4; ++e)
;             if (4 * q + e < i) sacc += Lv[e] * xv[4 * q + e];
;         }
;         xv[i] = sacc;
;       }
;       float* Dk = Tf + (16 * g4) * 68 + 16 * g4 + r16;
; #pragma unroll
;       for (int i = 0; i < 16; ++i) Dk[i * 68] = xv[i];
;     }
	ds_read_b128 v[48:51], v189 offset:272
	ds_read_b128 v[52:55], v189 offset:544
	ds_read_b128 v[56:59], v189 offset:816
	ds_read_b128 v[60:63], v189 offset:1088
	ds_read_b128 v[64:67], v189 offset:1360
	ds_read_b128 v[68:71], v189 offset:1376
	ds_read_b128 v[72:75], v189 offset:1632
	ds_read_b128 v[76:79], v189 offset:1648
	ds_read_b128 v[80:83], v189 offset:1904
	ds_read_b128 v[84:87], v189 offset:1920
	ds_read_b128 v[88:91], v189 offset:2176
	ds_read_b128 v[96:99], v189 offset:2192
	ds_read_b128 v[100:103], v189 offset:2448
	ds_read_b128 v[104:107], v189 offset:2464
	ds_read_b128 v[108:111], v189 offset:2480
	s_waitcnt lgkmcnt(14)
	v_fma_f32 v30, v190, v48, v191
	ds_read_b128 v[48:51], v189 offset:2720
	s_waitcnt lgkmcnt(14)
	v_fma_f32 v31, v190, v52, v253
	v_fmac_f32_e32 v31, v53, v30
	ds_read_b128 v[52:55], v189 offset:2736
	s_waitcnt lgkmcnt(14)
	v_fma_f32 v32, v190, v56, v254
	v_fmac_f32_e32 v32, v57, v30
	v_fmac_f32_e32 v32, v58, v31
	ds_read_b128 v[56:59], v189 offset:2752
	s_waitcnt lgkmcnt(14)
	v_fma_f32 v33, v190, v60, v255
	v_fmac_f32_e32 v33, v61, v30
	v_fmac_f32_e32 v33, v62, v31
	v_fmac_f32_e32 v33, v63, v32
	ds_read_b128 v[60:63], v189 offset:2992
	s_waitcnt lgkmcnt(13)
	v_fma_f32 v34, v190, v64, v241
	v_fmac_f32_e32 v34, v65, v30
	v_fmac_f32_e32 v34, v66, v31
	v_fmac_f32_e32 v34, v67, v32
	v_fmac_f32_e32 v34, v68, v33
	ds_read_b128 v[64:67], v189 offset:3008
	ds_read_b128 v[68:71], v189 offset:3024
	v_cmp_eq_u32_e32 vcc, 6, v174
	s_nop 1
	v_cndmask_b32_e64 v35, 0, 1.0, vcc
	s_waitcnt lgkmcnt(13)
	v_fma_f32 v35, v190, v72, v35
	v_fmac_f32_e32 v35, v73, v30
	v_fmac_f32_e32 v35, v74, v31
	v_fmac_f32_e32 v35, v75, v32
	v_fmac_f32_e32 v35, v76, v33
	v_fmac_f32_e32 v35, v77, v34
	ds_read_b128 v[72:75], v189 offset:3264
	ds_read_b128 v[76:79], v189 offset:3280
	v_cmp_eq_u32_e32 vcc, 7, v174
	s_nop 1
	v_cndmask_b32_e64 v36, 0, 1.0, vcc
	s_waitcnt lgkmcnt(13)
	v_fma_f32 v36, v190, v80, v36
	v_fmac_f32_e32 v36, v81, v30
	v_fmac_f32_e32 v36, v82, v31
	v_fmac_f32_e32 v36, v83, v32
	v_fmac_f32_e32 v36, v84, v33
	v_fmac_f32_e32 v36, v85, v34
	v_fmac_f32_e32 v36, v86, v35
	ds_read_b128 v[80:83], v189 offset:3296
	ds_read_b128 v[84:87], v189 offset:3536
	v_cmp_eq_u32_e32 vcc, 8, v174
	s_nop 1
	v_cndmask_b32_e64 v37, 0, 1.0, vcc
	s_waitcnt lgkmcnt(13)
	v_fma_f32 v37, v190, v88, v37
	v_fmac_f32_e32 v37, v89, v30
	v_fmac_f32_e32 v37, v90, v31
	v_fmac_f32_e32 v37, v91, v32
	v_fmac_f32_e32 v37, v96, v33
	v_fmac_f32_e32 v37, v97, v34
	v_fmac_f32_e32 v37, v98, v35
	v_fmac_f32_e32 v37, v99, v36
	ds_read_b128 v[88:91], v189 offset:3552
	ds_read_b128 v[96:99], v189 offset:3568
	v_cmp_eq_u32_e32 vcc, 9, v174
	s_nop 1
	v_cndmask_b32_e64 v38, 0, 1.0, vcc
	s_waitcnt lgkmcnt(12)
	v_fma_f32 v38, v190, v100, v38
	v_fmac_f32_e32 v38, v101, v30
	v_fmac_f32_e32 v38, v102, v31
	v_fmac_f32_e32 v38, v103, v32
	v_fmac_f32_e32 v38, v104, v33
	v_fmac_f32_e32 v38, v105, v34
	v_fmac_f32_e32 v38, v106, v35
	v_fmac_f32_e32 v38, v107, v36
	v_fmac_f32_e32 v38, v108, v37
	ds_read_b128 v[100:103], v189 offset:3584
	ds_read_b128 v[104:107], v189 offset:3808
	ds_read_b128 v[108:111], v189 offset:3824
	v_cmp_eq_u32_e32 vcc, 10, v174
	s_nop 1
	v_cndmask_b32_e64 v39, 0, 1.0, vcc
	s_waitcnt lgkmcnt(12)
	v_fma_f32 v39, v190, v48, v39
	v_fmac_f32_e32 v39, v49, v30
	v_fmac_f32_e32 v39, v50, v31
	v_fmac_f32_e32 v39, v51, v32
	v_fmac_f32_e32 v39, v52, v33
	v_fmac_f32_e32 v39, v53, v34
	v_fmac_f32_e32 v39, v54, v35
	v_fmac_f32_e32 v39, v55, v36
	v_fmac_f32_e32 v39, v56, v37
	v_fmac_f32_e32 v39, v57, v38
	ds_read_b128 v[48:51], v189 offset:3840
	ds_read_b128 v[52:55], v189 offset:3856
	ds_read_b128 v[56:59], v189 offset:4080
	v_cmp_eq_u32_e32 vcc, 11, v174
	s_nop 1
	v_cndmask_b32_e64 v40, 0, 1.0, vcc
	s_waitcnt lgkmcnt(12)
	v_fma_f32 v40, v190, v60, v40
	v_fmac_f32_e32 v40, v61, v30
	v_fmac_f32_e32 v40, v62, v31
	v_fmac_f32_e32 v40, v63, v32
	v_fmac_f32_e32 v40, v64, v33
	v_fmac_f32_e32 v40, v65, v34
	v_fmac_f32_e32 v40, v66, v35
	v_fmac_f32_e32 v40, v67, v36
	v_fmac_f32_e32 v40, v68, v37
	v_fmac_f32_e32 v40, v69, v38
	v_fmac_f32_e32 v40, v70, v39
	ds_read_b128 v[60:63], v189 offset:4096
	ds_read_b128 v[64:67], v189 offset:4112
	ds_read_b128 v[68:71], v189 offset:4128
	v_cmp_eq_u32_e32 vcc, 12, v174
	s_nop 1
	v_cndmask_b32_e64 v41, 0, 1.0, vcc
	s_waitcnt lgkmcnt(12)
	v_fma_f32 v41, v190, v72, v41
	v_fmac_f32_e32 v41, v73, v30
	v_fmac_f32_e32 v41, v74, v31
	v_fmac_f32_e32 v41, v75, v32
	v_fmac_f32_e32 v41, v76, v33
	v_fmac_f32_e32 v41, v77, v34
	v_fmac_f32_e32 v41, v78, v35
	v_fmac_f32_e32 v41, v79, v36
	v_fmac_f32_e32 v41, v80, v37
	v_fmac_f32_e32 v41, v81, v38
	v_fmac_f32_e32 v41, v82, v39
	v_fmac_f32_e32 v41, v83, v40
	v_cmp_eq_u32_e32 vcc, 13, v174
	s_nop 1
	v_cndmask_b32_e64 v28, 0, 1.0, vcc
	s_waitcnt lgkmcnt(8)
	v_fma_f32 v28, v190, v84, v28
	v_fmac_f32_e32 v28, v85, v30
	v_fmac_f32_e32 v28, v86, v31
	v_fmac_f32_e32 v28, v87, v32
	v_fmac_f32_e32 v28, v88, v33
	v_fmac_f32_e32 v28, v89, v34
	v_fmac_f32_e32 v28, v90, v35
	v_fmac_f32_e32 v28, v91, v36
	v_fmac_f32_e32 v28, v96, v37
	v_fmac_f32_e32 v28, v97, v38
	v_fmac_f32_e32 v28, v98, v39
	v_fmac_f32_e32 v28, v99, v40
	v_fmac_f32_e32 v28, v100, v41
	s_waitcnt lgkmcnt(4)
	v_fma_f32 v29, v190, v104, v204
	v_fmac_f32_e32 v29, v105, v30
	v_fmac_f32_e32 v29, v106, v31
	v_fmac_f32_e32 v29, v107, v32
	v_fmac_f32_e32 v29, v108, v33
	v_fmac_f32_e32 v29, v109, v34
	v_fmac_f32_e32 v29, v110, v35
	v_fmac_f32_e32 v29, v111, v36
	v_fmac_f32_e32 v29, v48, v37
	v_fmac_f32_e32 v29, v49, v38
	v_fmac_f32_e32 v29, v50, v39
	v_fmac_f32_e32 v29, v51, v40
	v_fmac_f32_e32 v29, v52, v41
	v_fmac_f32_e32 v29, v53, v28
	s_waitcnt lgkmcnt(0)
	v_fma_f32 v46, v190, v56, v205
	v_fmac_f32_e32 v46, v57, v30
	v_fmac_f32_e32 v46, v58, v31
	v_fmac_f32_e32 v46, v59, v32
	v_fmac_f32_e32 v46, v60, v33
	v_fmac_f32_e32 v46, v61, v34
	v_fmac_f32_e32 v46, v62, v35
	v_fmac_f32_e32 v46, v63, v36
	v_fmac_f32_e32 v46, v64, v37
	v_fmac_f32_e32 v46, v65, v38
	v_fmac_f32_e32 v46, v66, v39
	v_fmac_f32_e32 v46, v67, v40
	v_fmac_f32_e32 v46, v68, v41
	v_fmac_f32_e32 v46, v69, v28
	v_fmac_f32_e32 v46, v70, v29
	ds_write2_b32 v206, v190, v30 offset1:68
	ds_write2_b32 v206, v31, v32 offset0:136 offset1:204
	v_add_u32_e32 v18, 0x400, v206
	ds_write2_b32 v18, v33, v34 offset0:16 offset1:84
	ds_write2_b32 v18, v35, v36 offset0:152 offset1:220
	v_add_u32_e32 v18, 0x800, v206
	ds_write2_b32 v18, v37, v38 offset0:32 offset1:100
	ds_write2_b32 v18, v39, v40 offset0:168 offset1:236
	v_add_u32_e32 v18, 0xc00, v206
	ds_write2_b32 v18, v41, v28 offset0:48 offset1:116
	ds_write2_b32 v18, v29, v46 offset0:184 offset1:252
